# prep hyena-filter items: output scatter loop rewritten, 8 LDS reads batched per wait with hoisted invariant exec mask (was 64 serialized ds_read->store iterations)
# speedup vs baseline: 1.0080x; 1.0005x over previous
.LBB0_168:
	v_cvt_f32_u32_e32 v146, s80
	s_add_i32 s54, s80, -1
	s_sub_i32 s6, s61, 64
	v_cvt_f32_u32_e32 v147, s54
	v_mov_b32_e32 v82, s6
	v_mul_f32_e32 v146, 0xbb808081, v146
	v_lshl_add_u32 v142, v82, 2, s90
	ds_read_b128 v[82:85], v142 offset:37248
	ds_read_b128 v[86:89], v142 offset:37264
	ds_read_b128 v[90:93], v142 offset:37280
	ds_read_b128 v[94:97], v142 offset:37296
	ds_read_b128 v[98:101], v142 offset:37312
	ds_read_b128 v[102:105], v142 offset:37328
	ds_read_b128 v[106:109], v142 offset:37344
	ds_read_b128 v[110:113], v142 offset:37360
	ds_read_b128 v[114:117], v142 offset:37392
	ds_read_b128 v[118:121], v142 offset:37376
	ds_read_b128 v[122:125], v142 offset:37424
	ds_read_b128 v[126:129], v142 offset:37408
	ds_read_b128 v[130:133], v142 offset:37456
	ds_read_b128 v[134:137], v142 offset:37440
	ds_read_b128 v[138:141], v142 offset:37488
	ds_read_b128 v[142:145], v142 offset:37472
	v_mul_f32_e64 v148, |v68|, v146
	v_mul_f32_e32 v147, 0xbb808081, v147
	v_mul_f32_e32 v146, 0x3fb8aa3b, v148
	v_mul_f32_e64 v149, |v68|, v147
	v_rndne_f32_e32 v147, v146
	s_waitcnt vmcnt(62) lgkmcnt(14)
	v_mul_f32_e32 v156, v3, v83
	v_sub_f32_e32 v154, v146, v147
	v_cvt_i32_f32_e32 v155, v147
	s_waitcnt vmcnt(58)
	v_mul_f32_e32 v157, v39, v87
	s_waitcnt vmcnt(54) lgkmcnt(13)
	v_mul_f32_e32 v158, v43, v91
	s_waitcnt lgkmcnt(7)
	v_mov_b32_e32 v147, v114
	s_waitcnt lgkmcnt(6)
	v_mov_b32_e32 v114, v119
	v_mov_b32_e32 v119, v116
	v_mov_b32_e32 v116, v121
	s_waitcnt lgkmcnt(5)
	v_mov_b32_e32 v121, v122
	s_waitcnt lgkmcnt(4)
	v_mov_b32_e32 v122, v127
	v_mov_b32_e32 v127, v124
	v_mov_b32_e32 v124, v129
	s_waitcnt lgkmcnt(3)
	v_mov_b32_e32 v129, v130
	s_waitcnt lgkmcnt(2)
	v_mov_b32_e32 v130, v135
	v_fmac_f32_e32 v156, v1, v82
	v_fma_f32 v151, v148, s86, -v146
	v_mov_b32_e32 v146, v118
	v_mov_b32_e32 v118, v120
	v_mov_b32_e32 v120, v126
	v_mov_b32_e32 v126, v128
	v_mov_b32_e32 v128, v134
	v_fmac_f32_e32 v157, v38, v86
	v_fmac_f32_e32 v158, v42, v90
	s_waitcnt vmcnt(18)
	v_pk_mul_f32 v[86:87], v[14:15], v[122:123]
	s_waitcnt vmcnt(10)
	v_pk_mul_f32 v[90:91], v[22:23], v[130:131]
	v_fmac_f32_e32 v156, v36, v84
	v_mul_f32_e32 v159, v47, v95
	v_mov_b32_e32 v134, v136
	v_mov_b32_e32 v135, v132
	v_fmac_f32_e32 v157, v40, v88
	v_pk_fma_f32 v[86:87], v[12:13], v[120:121], v[86:87]
	v_pk_fma_f32 v[90:91], v[20:21], v[128:129], v[90:91]
	v_fmac_f32_e32 v156, v37, v85
	v_mul_f32_e32 v99, v51, v99
	v_fmac_f32_e32 v159, v46, v94
	v_fmac_f32_e32 v158, v44, v92
	v_fmac_f32_e32 v157, v41, v89
	v_pk_fma_f32 v[84:85], v[16:17], v[126:127], v[86:87]
	s_waitcnt vmcnt(9)
	v_pk_fma_f32 v[86:87], v[24:25], v[134:135], v[90:91]
	v_add_f32_e32 v90, 0, v156
	v_mul_f32_e32 v103, v55, v103
	v_fmac_f32_e32 v99, v50, v98
	v_fmac_f32_e32 v159, v48, v96
	v_fmac_f32_e32 v158, v45, v93
	v_add_f32_e32 v90, v90, v157
	v_mul_f32_e32 v107, v59, v107
	v_fmac_f32_e32 v103, v54, v102
	v_fmac_f32_e32 v99, v52, v100
	v_fmac_f32_e32 v159, v49, v97
	v_add_f32_e32 v90, v90, v158
	v_mul_f32_e32 v111, v65, v111
	v_fmac_f32_e32 v107, v58, v106
	v_fmac_f32_e32 v103, v56, v104
	v_fmac_f32_e32 v99, v53, v101
	v_add_f32_e32 v90, v90, v159
	v_fmac_f32_e32 v111, v64, v110
	v_pk_mul_f32 v[82:83], v[6:7], v[114:115]
	v_fmac_f32_e32 v107, v60, v108
	v_fmac_f32_e32 v103, v57, v105
	v_add_f32_e32 v90, v90, v99
	v_mul_f32_e32 v150, 0x3fb8aa3b, v149
	v_fmac_f32_e32 v111, v66, v112
	v_pk_fma_f32 v[82:83], v[4:5], v[146:147], v[82:83]
	v_fmac_f32_e32 v107, v63, v109
	v_add_f32_e32 v90, v90, v103
	v_fma_f32 v152, v149, s86, -v150
	v_rndne_f32_e32 v153, v150
	v_fmac_f32_e32 v111, v67, v113
	v_pk_fma_f32 v[82:83], v[8:9], v[118:119], v[82:83]
	v_add_f32_e32 v90, v90, v107
	v_fmac_f32_e32 v151, 0x32a5705f, v148
	s_waitcnt lgkmcnt(0)
	v_mov_b32_e32 v136, v142
	v_mov_b32_e32 v142, v144
	v_fmac_f32_e32 v152, 0x32a5705f, v149
	v_sub_f32_e32 v144, v150, v153
	v_pk_fma_f32 v[82:83], v[10:11], v[116:117], v[82:83]
	v_add_f32_e32 v90, v90, v111
	v_add_f32_e32 v150, v154, v151
	v_add_f32_e32 v98, v144, v152
	v_add_f32_e32 v82, v90, v82
	v_mov_b32_e32 v132, v137
	v_mov_b32_e32 v137, v138
	v_mov_b32_e32 v138, v143
	v_mov_b32_e32 v143, v140
	v_mov_b32_e32 v140, v145
	v_cvt_i32_f32_e32 v145, v153
	v_exp_f32_e32 v102, v150
	v_exp_f32_e32 v92, v98
	v_pk_fma_f32 v[84:85], v[18:19], v[124:125], v[84:85]
	v_add_f32_e32 v82, v82, v83
	s_waitcnt vmcnt(2)
	v_pk_mul_f32 v[94:95], v[30:31], v[138:139]
	v_add_f32_e32 v82, v82, v84
	v_pk_fma_f32 v[94:95], v[28:29], v[136:137], v[94:95]
	v_pk_fma_f32 v[86:87], v[26:27], v[132:133], v[86:87]
	v_add_f32_e32 v82, v82, v85
	s_add_i32 s7, s60, s61
	s_waitcnt vmcnt(1)
	v_pk_fma_f32 v[88:89], v[32:33], v[142:143], v[94:95]
	v_add_f32_e32 v82, v82, v86
	s_cmp_lg_u32 s7, 64
	s_waitcnt vmcnt(0)
	v_pk_fma_f32 v[88:89], v[34:35], v[140:141], v[88:89]
	v_ldexp_f32 v91, v102, v155
	v_cmp_ngt_f32_e32 vcc, s87, v148
	v_ldexp_f32 v92, v92, v145
	v_cmp_ngt_f32_e64 s[6:7], s87, v149
	v_add_f32_e32 v82, v82, v87
	v_cndmask_b32_e32 v91, 0, v91, vcc
	v_cmp_nlt_f32_e32 vcc, s85, v148
	v_cndmask_b32_e64 v92, 0, v92, s[6:7]
	v_cmp_nlt_f32_e64 s[6:7], s85, v149
	v_add_f32_e32 v82, v82, v88
	v_cndmask_b32_e32 v146, v71, v91, vcc
	v_cndmask_b32_e64 v91, v71, v92, s[6:7]
	v_add_f32_e32 v82, v82, v89
	s_cselect_b64 s[54:55], -1, 0
	v_mul_f32_e32 v82, v91, v82
	v_add_f32_e64 v83, v80, |v82|
	s_or_b64 vcc, s[0:1], s[54:55]
	v_bfe_u32 v84, v82, 16, 1
	v_mov_b32_e32 v81, s61
	v_cndmask_b32_e32 v147, v80, v83, vcc
	v_add3_u32 v80, v82, v84, s95
	ds_write_b16_d16_hi v69, v80
	s_addk_i32 s61, 0x80
	v_lshl_add_u32 v140, v81, 2, s90
	ds_read_b128 v[80:83], v140 offset:37248
	ds_read_b128 v[84:87], v140 offset:37264
	ds_read_b128 v[88:91], v140 offset:37280
	ds_read_b128 v[92:95], v140 offset:37296
	ds_read_b128 v[96:99], v140 offset:37312
	ds_read_b128 v[100:103], v140 offset:37328
	ds_read_b128 v[104:107], v140 offset:37344
	ds_read_b128 v[108:111], v140 offset:37360
	ds_read_b128 v[112:115], v140 offset:37392
	ds_read_b128 v[116:119], v140 offset:37376
	ds_read_b128 v[120:123], v140 offset:37424
	ds_read_b128 v[124:127], v140 offset:37408
	ds_read_b128 v[128:131], v140 offset:37456
	ds_read_b128 v[132:135], v140 offset:37440
	ds_read_b128 v[136:139], v140 offset:37488
	ds_read_b128 v[140:143], v140 offset:37472
	s_waitcnt lgkmcnt(14)
	v_mul_f32_e32 v148, v3, v81
	v_mul_f32_e32 v149, v39, v85
	s_waitcnt lgkmcnt(13)
	v_mul_f32_e32 v150, v43, v89
	s_waitcnt lgkmcnt(7)
	v_mov_b32_e32 v145, v112
	s_waitcnt lgkmcnt(6)
	v_mov_b32_e32 v112, v117
	v_mov_b32_e32 v117, v114
	v_mov_b32_e32 v114, v119
	s_waitcnt lgkmcnt(5)
	v_mov_b32_e32 v119, v120
	s_waitcnt lgkmcnt(4)
	v_mov_b32_e32 v120, v125
	v_mov_b32_e32 v125, v122
	v_mov_b32_e32 v122, v127
	s_waitcnt lgkmcnt(3)
	v_mov_b32_e32 v127, v128
	s_waitcnt lgkmcnt(2)
	v_mov_b32_e32 v128, v133
	v_fmac_f32_e32 v148, v1, v80
	v_mov_b32_e32 v144, v116
	v_mov_b32_e32 v116, v118
	v_mov_b32_e32 v118, v124
	v_mov_b32_e32 v124, v126
	v_mov_b32_e32 v126, v132
	v_fmac_f32_e32 v149, v38, v84
	v_fmac_f32_e32 v150, v42, v88
	v_pk_mul_f32 v[84:85], v[14:15], v[120:121]
	v_pk_mul_f32 v[88:89], v[22:23], v[128:129]
	v_fmac_f32_e32 v148, v36, v82
	v_mul_f32_e32 v151, v47, v93
	v_mov_b32_e32 v132, v134
	v_mov_b32_e32 v133, v130
	v_fmac_f32_e32 v149, v40, v86
	v_pk_fma_f32 v[84:85], v[12:13], v[118:119], v[84:85]
	v_pk_fma_f32 v[88:89], v[20:21], v[126:127], v[88:89]
	v_fmac_f32_e32 v148, v37, v83
	v_mul_f32_e32 v97, v51, v97
	v_fmac_f32_e32 v151, v46, v92
	v_fmac_f32_e32 v150, v44, v90
	v_fmac_f32_e32 v149, v41, v87
	v_pk_fma_f32 v[82:83], v[16:17], v[124:125], v[84:85]
	v_pk_fma_f32 v[84:85], v[24:25], v[132:133], v[88:89]
	v_add_f32_e32 v88, 0, v148
	v_mul_f32_e32 v101, v55, v101
	v_fmac_f32_e32 v97, v50, v96
	v_fmac_f32_e32 v151, v48, v94
	v_fmac_f32_e32 v150, v45, v91
	v_add_f32_e32 v88, v88, v149
	v_mul_f32_e32 v105, v59, v105
	v_fmac_f32_e32 v101, v54, v100
	v_fmac_f32_e32 v97, v52, v98
	v_fmac_f32_e32 v151, v49, v95
	v_add_f32_e32 v88, v88, v150
	v_mul_f32_e32 v109, v65, v109
	v_fmac_f32_e32 v105, v58, v104
	v_fmac_f32_e32 v101, v56, v102
	v_fmac_f32_e32 v97, v53, v99
	v_add_f32_e32 v88, v88, v151
	v_fmac_f32_e32 v109, v64, v108
	v_pk_mul_f32 v[80:81], v[6:7], v[112:113]
	v_fmac_f32_e32 v105, v60, v106
	v_fmac_f32_e32 v101, v57, v103
	v_add_f32_e32 v88, v88, v97
	v_fmac_f32_e32 v109, v66, v110
	v_pk_fma_f32 v[80:81], v[4:5], v[144:145], v[80:81]
	v_fmac_f32_e32 v105, v63, v107
	v_add_f32_e32 v88, v88, v101
	v_fmac_f32_e32 v109, v67, v111
	v_pk_fma_f32 v[80:81], v[8:9], v[116:117], v[80:81]
	v_add_f32_e32 v88, v88, v105
	v_pk_fma_f32 v[80:81], v[10:11], v[114:115], v[80:81]
	v_add_f32_e32 v88, v88, v109
	v_add_f32_e32 v80, v88, v80
	v_mov_b32_e32 v130, v135
	s_waitcnt lgkmcnt(1)
	v_mov_b32_e32 v135, v136
	s_waitcnt lgkmcnt(0)
	v_mov_b32_e32 v136, v141
	v_pk_fma_f32 v[82:83], v[18:19], v[122:123], v[82:83]
	v_add_f32_e32 v80, v80, v81
	v_mov_b32_e32 v134, v140
	v_pk_mul_f32 v[92:93], v[30:31], v[136:137]
	v_add_f32_e32 v80, v80, v82
	v_mov_b32_e32 v140, v142
	v_mov_b32_e32 v141, v138
	v_pk_fma_f32 v[92:93], v[28:29], v[134:135], v[92:93]
	v_pk_fma_f32 v[84:85], v[26:27], v[130:131], v[84:85]
	v_add_f32_e32 v80, v80, v83
	v_mov_b32_e32 v138, v143
	v_pk_fma_f32 v[86:87], v[32:33], v[140:141], v[92:93]
	v_add_f32_e32 v80, v80, v84
	v_pk_fma_f32 v[86:87], v[34:35], v[138:139], v[86:87]
	v_add_f32_e32 v80, v80, v85
	v_add_f32_e32 v80, v80, v86
	v_add_f32_e32 v80, v80, v87
	v_mul_f32_e32 v81, v146, v80
	v_bfe_u32 v82, v81, 16, 1
	s_add_i32 s80, s80, 2
	v_add_f32_e64 v80, v147, |v81|
	v_add3_u32 v81, v81, v82, s95
	s_cmpk_eq_i32 s61, 0x840
	ds_write_b16_d16_hi v69, v81 offset:2
	v_add_u32_e32 v69, 4, v69
	s_cbranch_scc0 .LBB0_168
	v_add_u32_e32 v2, s58, v2
	v_ashrrev_i32_e32 v3, 31, v2
	v_lshl_add_u64 v[2:3], v[2:3], 2, s[34:35]
	s_movk_i32 s36, 0x100
	s_mov_b64 s[6:7], 0
	s_and_b64 vcc, exec, s[10:11]
	global_store_dword v[2:3], v80, off
	s_cbranch_vccz .LBB0_167
	v_ashrrev_i32_e32 v1, 5, v0
	s_movk_i32 s6, 0x200
	s_lshr_b32 s56, s56, 1
	v_cmp_gt_i32_e32 vcc, s6, v1
	s_waitcnt lgkmcnt(0)
	s_barrier
	s_and_saveexec_b64 s[6:7], vcc
	s_cbranch_execz .LBB0_175
	v_and_b32_e32 v4, 31, v0
	v_or_b32_e32 v2, s57, v4
	v_sub_u32_e32 v3, 0, v2
	v_cmp_ne_u32_e32 vcc, 0, v2
	v_cndmask_b32_e64 v2, v2, v3, s[0:1]
	s_mov_b32 s36, s44
	v_readlane_b32 s44, v253, 32
	s_lshl_b32 s10, s46, 10
	s_lshl_b32 s11, s56, 9
	v_ashrrev_i32_e32 v3, 31, v2
	v_readlane_b32 s45, v253, 33
	v_mul_lo_u32 v5, v1, s38
	v_lshlrev_b32_e32 v4, 1, v4
	s_or_b64 s[8:9], s[0:1], vcc
	v_lshl_add_u64 v[2:3], v[2:3], 1, s[44:45]
	s_mov_b32 s44, s36
	s_or_b32 s36, s10, s11
	v_add3_u32 v4, v5, v4, s90
	s_and_saveexec_b64 s[54:55], s[8:9]
	s_cbranch_execz .Lfsc0_done
	v_add_u32_e32 v6, s36, v1
	s_movk_i32 s40, 0x420
	v_mad_i64_i32 v[130:131], s[48:49], v6, s40, v[2:3]
	s_mov_b64 s[100:101], 0x2100
	s_mov_b32 s10, 8
.Lfsc0_loop:
	ds_read_u16 v146, v4
	ds_read_u16 v147, v4 offset:544
	ds_read_u16 v148, v4 offset:1088
	ds_read_u16 v149, v4 offset:1632
	ds_read_u16 v150, v4 offset:2176
	ds_read_u16 v151, v4 offset:2720
	ds_read_u16 v152, v4 offset:3264
	ds_read_u16 v153, v4 offset:3808
	v_lshl_add_u64 v[132:133], v[130:131], 0, s[100:101]
	v_lshl_add_u64 v[134:135], v[132:133], 0, s[100:101]
	v_lshl_add_u64 v[136:137], v[134:135], 0, s[100:101]
	v_lshl_add_u64 v[138:139], v[136:137], 0, s[100:101]
	v_lshl_add_u64 v[140:141], v[138:139], 0, s[100:101]
	v_lshl_add_u64 v[142:143], v[140:141], 0, s[100:101]
	v_lshl_add_u64 v[144:145], v[142:143], 0, s[100:101]
	s_waitcnt lgkmcnt(7)
	global_store_short v[130:131], v146, off offset:512
	s_waitcnt lgkmcnt(6)
	global_store_short v[132:133], v147, off offset:512
	s_waitcnt lgkmcnt(5)
	global_store_short v[134:135], v148, off offset:512
	s_waitcnt lgkmcnt(4)
	global_store_short v[136:137], v149, off offset:512
	s_waitcnt lgkmcnt(3)
	global_store_short v[138:139], v150, off offset:512
	s_waitcnt lgkmcnt(2)
	global_store_short v[140:141], v151, off offset:512
	s_waitcnt lgkmcnt(1)
	global_store_short v[142:143], v152, off offset:512
	s_waitcnt lgkmcnt(0)
	global_store_short v[144:145], v153, off offset:512
	v_mov_b32_e32 v6, v144
	v_mov_b32_e32 v7, v145
	v_lshl_add_u64 v[130:131], v[144:145], 0, s[100:101]
	v_add_u32_e32 v4, 0x1100, v4
	s_add_i32 s10, s10, -1
	s_cmp_lg_u32 s10, 0
	s_cbranch_scc1 .Lfsc0_loop
.Lfsc0_done:
	s_or_b64 exec, exec, s[54:55]
	s_movk_i32 s40, 0x1f7
	v_add_u32_e32 v1, 0x200, v1
	v_mov_b32_e32 v5, v1
	s_mov_b64 s[10:11], exec

.LBB0_317:
	v_cvt_f32_u32_e32 v146, s80
	s_add_i32 s54, s80, -1
	s_sub_i32 s6, s61, 64
	v_cvt_f32_u32_e32 v147, s54
	v_mov_b32_e32 v82, s6
	v_mul_f32_e32 v146, 0xba802008, v146
	v_lshl_add_u32 v142, v82, 2, s90
	ds_read_b128 v[82:85], v142 offset:37248
	ds_read_b128 v[86:89], v142 offset:37264
	ds_read_b128 v[90:93], v142 offset:37280
	ds_read_b128 v[94:97], v142 offset:37296
	ds_read_b128 v[98:101], v142 offset:37312
	ds_read_b128 v[102:105], v142 offset:37328
	ds_read_b128 v[106:109], v142 offset:37344
	ds_read_b128 v[110:113], v142 offset:37360
	ds_read_b128 v[114:117], v142 offset:37392
	ds_read_b128 v[118:121], v142 offset:37376
	ds_read_b128 v[122:125], v142 offset:37424
	ds_read_b128 v[126:129], v142 offset:37408
	ds_read_b128 v[130:133], v142 offset:37456
	ds_read_b128 v[134:137], v142 offset:37440
	ds_read_b128 v[138:141], v142 offset:37488
	ds_read_b128 v[142:145], v142 offset:37472
	v_mul_f32_e64 v148, |v68|, v146
	v_mul_f32_e32 v147, 0xba802008, v147
	v_mul_f32_e32 v146, 0x3fb8aa3b, v148
	v_mul_f32_e64 v149, |v68|, v147
	v_rndne_f32_e32 v147, v146
	s_waitcnt vmcnt(62) lgkmcnt(14)
	v_mul_f32_e32 v156, v3, v83
	v_sub_f32_e32 v154, v146, v147
	v_cvt_i32_f32_e32 v155, v147
	s_waitcnt vmcnt(58)
	v_mul_f32_e32 v157, v39, v87
	s_waitcnt vmcnt(54) lgkmcnt(13)
	v_mul_f32_e32 v158, v43, v91
	s_waitcnt lgkmcnt(7)
	v_mov_b32_e32 v147, v114
	s_waitcnt lgkmcnt(6)
	v_mov_b32_e32 v114, v119
	v_mov_b32_e32 v119, v116
	v_mov_b32_e32 v116, v121
	s_waitcnt lgkmcnt(5)
	v_mov_b32_e32 v121, v122
	s_waitcnt lgkmcnt(4)
	v_mov_b32_e32 v122, v127
	v_mov_b32_e32 v127, v124
	v_mov_b32_e32 v124, v129
	s_waitcnt lgkmcnt(3)
	v_mov_b32_e32 v129, v130
	s_waitcnt lgkmcnt(2)
	v_mov_b32_e32 v130, v135
	v_fmac_f32_e32 v156, v1, v82
	v_fma_f32 v151, v148, s86, -v146
	v_mov_b32_e32 v146, v118
	v_mov_b32_e32 v118, v120
	v_mov_b32_e32 v120, v126
	v_mov_b32_e32 v126, v128
	v_mov_b32_e32 v128, v134
	v_fmac_f32_e32 v157, v38, v86
	v_fmac_f32_e32 v158, v42, v90
	s_waitcnt vmcnt(18)
	v_pk_mul_f32 v[86:87], v[14:15], v[122:123]
	s_waitcnt vmcnt(10)
	v_pk_mul_f32 v[90:91], v[22:23], v[130:131]
	v_fmac_f32_e32 v156, v36, v84
	v_mul_f32_e32 v159, v47, v95
	v_mov_b32_e32 v134, v136
	v_mov_b32_e32 v135, v132
	v_fmac_f32_e32 v157, v40, v88
	v_pk_fma_f32 v[86:87], v[12:13], v[120:121], v[86:87]
	v_pk_fma_f32 v[90:91], v[20:21], v[128:129], v[90:91]
	v_fmac_f32_e32 v156, v37, v85
	v_mul_f32_e32 v99, v51, v99
	v_fmac_f32_e32 v159, v46, v94
	v_fmac_f32_e32 v158, v44, v92
	v_fmac_f32_e32 v157, v41, v89
	v_pk_fma_f32 v[84:85], v[16:17], v[126:127], v[86:87]
	s_waitcnt vmcnt(9)
	v_pk_fma_f32 v[86:87], v[24:25], v[134:135], v[90:91]
	v_add_f32_e32 v90, 0, v156
	v_mul_f32_e32 v103, v55, v103
	v_fmac_f32_e32 v99, v50, v98
	v_fmac_f32_e32 v159, v48, v96
	v_fmac_f32_e32 v158, v45, v93
	v_add_f32_e32 v90, v90, v157
	v_mul_f32_e32 v107, v59, v107
	v_fmac_f32_e32 v103, v54, v102
	v_fmac_f32_e32 v99, v52, v100
	v_fmac_f32_e32 v159, v49, v97
	v_add_f32_e32 v90, v90, v158
	v_mul_f32_e32 v111, v65, v111
	v_fmac_f32_e32 v107, v58, v106
	v_fmac_f32_e32 v103, v56, v104
	v_fmac_f32_e32 v99, v53, v101
	v_add_f32_e32 v90, v90, v159
	v_fmac_f32_e32 v111, v64, v110
	v_pk_mul_f32 v[82:83], v[6:7], v[114:115]
	v_fmac_f32_e32 v107, v60, v108
	v_fmac_f32_e32 v103, v57, v105
	v_add_f32_e32 v90, v90, v99
	v_mul_f32_e32 v150, 0x3fb8aa3b, v149
	v_fmac_f32_e32 v111, v66, v112
	v_pk_fma_f32 v[82:83], v[4:5], v[146:147], v[82:83]
	v_fmac_f32_e32 v107, v63, v109
	v_add_f32_e32 v90, v90, v103
	v_fma_f32 v152, v149, s86, -v150
	v_rndne_f32_e32 v153, v150
	v_fmac_f32_e32 v111, v67, v113
	v_pk_fma_f32 v[82:83], v[8:9], v[118:119], v[82:83]
	v_add_f32_e32 v90, v90, v107
	v_fmac_f32_e32 v151, 0x32a5705f, v148
	s_waitcnt lgkmcnt(0)
	v_mov_b32_e32 v136, v142
	v_mov_b32_e32 v142, v144
	v_fmac_f32_e32 v152, 0x32a5705f, v149
	v_sub_f32_e32 v144, v150, v153
	v_pk_fma_f32 v[82:83], v[10:11], v[116:117], v[82:83]
	v_add_f32_e32 v90, v90, v111
	v_add_f32_e32 v150, v154, v151
	v_add_f32_e32 v98, v144, v152
	v_add_f32_e32 v82, v90, v82
	v_mov_b32_e32 v132, v137
	v_mov_b32_e32 v137, v138
	v_mov_b32_e32 v138, v143
	v_mov_b32_e32 v143, v140
	v_mov_b32_e32 v140, v145
	v_cvt_i32_f32_e32 v145, v153
	v_exp_f32_e32 v102, v150
	v_exp_f32_e32 v92, v98
	v_pk_fma_f32 v[84:85], v[18:19], v[124:125], v[84:85]
	v_add_f32_e32 v82, v82, v83
	s_waitcnt vmcnt(2)
	v_pk_mul_f32 v[94:95], v[30:31], v[138:139]
	v_add_f32_e32 v82, v82, v84
	v_pk_fma_f32 v[94:95], v[28:29], v[136:137], v[94:95]
	v_pk_fma_f32 v[86:87], v[26:27], v[132:133], v[86:87]
	v_add_f32_e32 v82, v82, v85
	s_add_i32 s7, s60, s61
	s_waitcnt vmcnt(1)
	v_pk_fma_f32 v[88:89], v[32:33], v[142:143], v[94:95]
	v_add_f32_e32 v82, v82, v86
	s_cmp_lg_u32 s7, 64
	s_waitcnt vmcnt(0)
	v_pk_fma_f32 v[88:89], v[34:35], v[140:141], v[88:89]
	v_ldexp_f32 v91, v102, v155
	v_cmp_ngt_f32_e32 vcc, s87, v148
	v_ldexp_f32 v92, v92, v145
	v_cmp_ngt_f32_e64 s[6:7], s87, v149
	v_add_f32_e32 v82, v82, v87
	v_cndmask_b32_e32 v91, 0, v91, vcc
	v_cmp_nlt_f32_e32 vcc, s85, v148
	v_cndmask_b32_e64 v92, 0, v92, s[6:7]
	v_cmp_nlt_f32_e64 s[6:7], s85, v149
	v_add_f32_e32 v82, v82, v88
	v_cndmask_b32_e32 v146, v71, v91, vcc
	v_cndmask_b32_e64 v91, v71, v92, s[6:7]
	v_add_f32_e32 v82, v82, v89
	s_cselect_b64 s[54:55], -1, 0
	v_mul_f32_e32 v82, v91, v82
	v_add_f32_e64 v83, v80, |v82|
	s_or_b64 vcc, s[0:1], s[54:55]
	v_bfe_u32 v84, v82, 16, 1
	v_mov_b32_e32 v81, s61
	v_cndmask_b32_e32 v147, v80, v83, vcc
	v_add3_u32 v80, v82, v84, s95
	ds_write_b16_d16_hi v69, v80
	s_addk_i32 s61, 0x80
	v_lshl_add_u32 v140, v81, 2, s90
	ds_read_b128 v[80:83], v140 offset:37248
	ds_read_b128 v[84:87], v140 offset:37264
	ds_read_b128 v[88:91], v140 offset:37280
	ds_read_b128 v[92:95], v140 offset:37296
	ds_read_b128 v[96:99], v140 offset:37312
	ds_read_b128 v[100:103], v140 offset:37328
	ds_read_b128 v[104:107], v140 offset:37344
	ds_read_b128 v[108:111], v140 offset:37360
	ds_read_b128 v[112:115], v140 offset:37392
	ds_read_b128 v[116:119], v140 offset:37376
	ds_read_b128 v[120:123], v140 offset:37424
	ds_read_b128 v[124:127], v140 offset:37408
	ds_read_b128 v[128:131], v140 offset:37456
	ds_read_b128 v[132:135], v140 offset:37440
	ds_read_b128 v[136:139], v140 offset:37488
	ds_read_b128 v[140:143], v140 offset:37472
	s_waitcnt lgkmcnt(14)
	v_mul_f32_e32 v148, v3, v81
	v_mul_f32_e32 v149, v39, v85
	s_waitcnt lgkmcnt(13)
	v_mul_f32_e32 v150, v43, v89
	s_waitcnt lgkmcnt(7)
	v_mov_b32_e32 v145, v112
	s_waitcnt lgkmcnt(6)
	v_mov_b32_e32 v112, v117
	v_mov_b32_e32 v117, v114
	v_mov_b32_e32 v114, v119
	s_waitcnt lgkmcnt(5)
	v_mov_b32_e32 v119, v120
	s_waitcnt lgkmcnt(4)
	v_mov_b32_e32 v120, v125
	v_mov_b32_e32 v125, v122
	v_mov_b32_e32 v122, v127
	s_waitcnt lgkmcnt(3)
	v_mov_b32_e32 v127, v128
	s_waitcnt lgkmcnt(2)
	v_mov_b32_e32 v128, v133
	v_fmac_f32_e32 v148, v1, v80
	v_mov_b32_e32 v144, v116
	v_mov_b32_e32 v116, v118
	v_mov_b32_e32 v118, v124
	v_mov_b32_e32 v124, v126
	v_mov_b32_e32 v126, v132
	v_fmac_f32_e32 v149, v38, v84
	v_fmac_f32_e32 v150, v42, v88
	v_pk_mul_f32 v[84:85], v[14:15], v[120:121]
	v_pk_mul_f32 v[88:89], v[22:23], v[128:129]
	v_fmac_f32_e32 v148, v36, v82
	v_mul_f32_e32 v151, v47, v93
	v_mov_b32_e32 v132, v134
	v_mov_b32_e32 v133, v130
	v_fmac_f32_e32 v149, v40, v86
	v_pk_fma_f32 v[84:85], v[12:13], v[118:119], v[84:85]
	v_pk_fma_f32 v[88:89], v[20:21], v[126:127], v[88:89]
	v_fmac_f32_e32 v148, v37, v83
	v_mul_f32_e32 v97, v51, v97
	v_fmac_f32_e32 v151, v46, v92
	v_fmac_f32_e32 v150, v44, v90
	v_fmac_f32_e32 v149, v41, v87
	v_pk_fma_f32 v[82:83], v[16:17], v[124:125], v[84:85]
	v_pk_fma_f32 v[84:85], v[24:25], v[132:133], v[88:89]
	v_add_f32_e32 v88, 0, v148
	v_mul_f32_e32 v101, v55, v101
	v_fmac_f32_e32 v97, v50, v96
	v_fmac_f32_e32 v151, v48, v94
	v_fmac_f32_e32 v150, v45, v91
	v_add_f32_e32 v88, v88, v149
	v_mul_f32_e32 v105, v59, v105
	v_fmac_f32_e32 v101, v54, v100
	v_fmac_f32_e32 v97, v52, v98
	v_fmac_f32_e32 v151, v49, v95
	v_add_f32_e32 v88, v88, v150
	v_mul_f32_e32 v109, v65, v109
	v_fmac_f32_e32 v105, v58, v104
	v_fmac_f32_e32 v101, v56, v102
	v_fmac_f32_e32 v97, v53, v99
	v_add_f32_e32 v88, v88, v151
	v_fmac_f32_e32 v109, v64, v108
	v_pk_mul_f32 v[80:81], v[6:7], v[112:113]
	v_fmac_f32_e32 v105, v60, v106
	v_fmac_f32_e32 v101, v57, v103
	v_add_f32_e32 v88, v88, v97
	v_fmac_f32_e32 v109, v66, v110
	v_pk_fma_f32 v[80:81], v[4:5], v[144:145], v[80:81]
	v_fmac_f32_e32 v105, v63, v107
	v_add_f32_e32 v88, v88, v101
	v_fmac_f32_e32 v109, v67, v111
	v_pk_fma_f32 v[80:81], v[8:9], v[116:117], v[80:81]
	v_add_f32_e32 v88, v88, v105
	v_pk_fma_f32 v[80:81], v[10:11], v[114:115], v[80:81]
	v_add_f32_e32 v88, v88, v109
	v_add_f32_e32 v80, v88, v80
	v_mov_b32_e32 v130, v135
	s_waitcnt lgkmcnt(1)
	v_mov_b32_e32 v135, v136
	s_waitcnt lgkmcnt(0)
	v_mov_b32_e32 v136, v141
	v_pk_fma_f32 v[82:83], v[18:19], v[122:123], v[82:83]
	v_add_f32_e32 v80, v80, v81
	v_mov_b32_e32 v134, v140
	v_pk_mul_f32 v[92:93], v[30:31], v[136:137]
	v_add_f32_e32 v80, v80, v82
	v_mov_b32_e32 v140, v142
	v_mov_b32_e32 v141, v138
	v_pk_fma_f32 v[92:93], v[28:29], v[134:135], v[92:93]
	v_pk_fma_f32 v[84:85], v[26:27], v[130:131], v[84:85]
	v_add_f32_e32 v80, v80, v83
	v_mov_b32_e32 v138, v143
	v_pk_fma_f32 v[86:87], v[32:33], v[140:141], v[92:93]
	v_add_f32_e32 v80, v80, v84
	v_pk_fma_f32 v[86:87], v[34:35], v[138:139], v[86:87]
	v_add_f32_e32 v80, v80, v85
	v_add_f32_e32 v80, v80, v86
	v_add_f32_e32 v80, v80, v87
	v_mul_f32_e32 v81, v146, v80
	v_bfe_u32 v82, v81, 16, 1
	s_add_i32 s80, s80, 2
	v_add_f32_e64 v80, v147, |v81|
	v_add3_u32 v81, v81, v82, s95
	s_cmpk_eq_i32 s61, 0x840
	ds_write_b16_d16_hi v69, v81 offset:2
	v_add_u32_e32 v69, 4, v69
	s_cbranch_scc0 .LBB0_317
	v_add_u32_e32 v2, s58, v2
	v_ashrrev_i32_e32 v3, 31, v2
	v_lshl_add_u64 v[2:3], v[2:3], 2, s[34:35]
	s_movk_i32 s36, 0x100
	s_mov_b64 s[6:7], 0
	s_and_b64 vcc, exec, s[10:11]
	global_store_dword v[2:3], v80, off
	s_cbranch_vccz .LBB0_316
	v_ashrrev_i32_e32 v1, 5, v0
	s_movk_i32 s6, 0x200
	s_lshr_b32 s56, s56, 1
	v_cmp_gt_i32_e32 vcc, s6, v1
	s_waitcnt lgkmcnt(0)
	s_barrier
	s_and_saveexec_b64 s[6:7], vcc
	s_cbranch_execz .LBB0_324
	v_and_b32_e32 v4, 31, v0
	v_or_b32_e32 v2, s57, v4
	v_sub_u32_e32 v3, 0, v2
	v_cmp_ne_u32_e32 vcc, 0, v2
	v_cndmask_b32_e64 v2, v2, v3, s[0:1]
	s_mov_b32 s36, s44
	v_readlane_b32 s44, v253, 36
	s_lshl_b32 s10, s46, 10
	s_lshl_b32 s11, s56, 9
	v_ashrrev_i32_e32 v3, 31, v2
	v_readlane_b32 s45, v253, 37
	v_mul_lo_u32 v5, v1, s38
	v_lshlrev_b32_e32 v4, 1, v4
	s_or_b64 s[8:9], s[0:1], vcc
	v_lshl_add_u64 v[2:3], v[2:3], 1, s[44:45]
	s_mov_b32 s44, s36
	s_or_b32 s36, s10, s11
	v_add3_u32 v4, v5, v4, s90
	s_and_saveexec_b64 s[54:55], s[8:9]
	s_cbranch_execz .Lfsc1_done
	v_add_u32_e32 v6, s36, v1
	s_movk_i32 s40, 0x1020
	v_mad_i64_i32 v[130:131], s[48:49], v6, s40, v[2:3]
	s_mov_b64 s[100:101], 0x8100
	s_mov_b32 s10, 8
.Lfsc1_loop:
	ds_read_u16 v146, v4
	ds_read_u16 v147, v4 offset:544
	ds_read_u16 v148, v4 offset:1088
	ds_read_u16 v149, v4 offset:1632
	ds_read_u16 v150, v4 offset:2176
	ds_read_u16 v151, v4 offset:2720
	ds_read_u16 v152, v4 offset:3264
	ds_read_u16 v153, v4 offset:3808
	v_lshl_add_u64 v[132:133], v[130:131], 0, s[100:101]
	v_lshl_add_u64 v[134:135], v[132:133], 0, s[100:101]
	v_lshl_add_u64 v[136:137], v[134:135], 0, s[100:101]
	v_lshl_add_u64 v[138:139], v[136:137], 0, s[100:101]
	v_lshl_add_u64 v[140:141], v[138:139], 0, s[100:101]
	v_lshl_add_u64 v[142:143], v[140:141], 0, s[100:101]
	v_lshl_add_u64 v[144:145], v[142:143], 0, s[100:101]
	s_waitcnt lgkmcnt(7)
	global_store_short v[130:131], v146, off offset:2048
	s_waitcnt lgkmcnt(6)
	global_store_short v[132:133], v147, off offset:2048
	s_waitcnt lgkmcnt(5)
	global_store_short v[134:135], v148, off offset:2048
	s_waitcnt lgkmcnt(4)
	global_store_short v[136:137], v149, off offset:2048
	s_waitcnt lgkmcnt(3)
	global_store_short v[138:139], v150, off offset:2048
	s_waitcnt lgkmcnt(2)
	global_store_short v[140:141], v151, off offset:2048
	s_waitcnt lgkmcnt(1)
	global_store_short v[142:143], v152, off offset:2048
	s_waitcnt lgkmcnt(0)
	global_store_short v[144:145], v153, off offset:2048
	v_mov_b32_e32 v6, v144
	v_mov_b32_e32 v7, v145
	v_lshl_add_u64 v[130:131], v[144:145], 0, s[100:101]
	v_add_u32_e32 v4, 0x1100, v4
	s_add_i32 s10, s10, -1
	s_cmp_lg_u32 s10, 0
	s_cbranch_scc1 .Lfsc1_loop
